# DeltaNet chunk scan: the 8 prefetch loads moved behind the barrier now follow the 12 batched LDS fragment reads (issued in the LDS-latency shadow) instead of preceding them
# speedup vs baseline: 1.0076x; 1.0076x over previous
.LBB0_286:
	v_add_u32_e32 v101, v43, v107
	s_add_u32 s18, s94, s10
	s_waitcnt lgkmcnt(0)
	s_barrier
	s_waitcnt vmcnt(4)
	v_perm_b32 v99, v147, v103, s78
	v_perm_b32 v97, v146, v105, s78
	ds_write_b128 v76, v[2:5]
	ds_write_b128 v101, v[6:9] offset:34816
	ds_write_b128 v76, v[10:13] offset:53248
	ds_write_b128 v78, v[14:17]
	ds_write_b128 v145, v[18:21] offset:34816
	ds_write_b128 v78, v[22:25] offset:53248
	ds_write_b128 v129, v[26:29]
	v_lshl_add_u64 v[2:3], s[94:95], 0, v[108:109]
	v_lshl_add_u64 v[6:7], s[94:95], 0, v[110:111]
	v_lshl_add_u64 v[10:11], s[94:95], 0, v[126:127]
	v_lshl_add_u64 v[14:15], s[94:95], 0, v[114:115]
	v_lshl_add_u64 v[18:19], s[94:95], 0, v[116:117]
	v_lshl_add_u64 v[22:23], s[94:95], 0, v[124:125]
	v_lshl_add_u64 v[26:27], s[94:95], 0, v[120:121]
	v_lshl_add_u64 v[146:147], s[94:95], 0, v[122:123]
	v_lshl_add_u64 v[148:149], s[94:95], 0, v[118:119]
	s_addc_u32 s19, s95, s12
	v_mov_b32_e32 v128, v106
	global_load_dwordx4 v[2:5], v[2:3], off
	v_pk_mul_f32 v[32:33], v[32:33], v[128:129] op_sel_hi:[1,0]
	global_load_dwordx4 v[6:9], v[6:7], off
	v_pk_mul_f32 v[30:31], v[30:31], v[128:129] op_sel_hi:[1,0]
	global_load_dwordx4 v[10:13], v[10:11], off
	v_pk_mul_f32 v[36:37], v[36:37], v[128:129] op_sel_hi:[1,0]
	global_load_dwordx4 v[14:17], v[14:15], off
	v_pk_mul_f32 v[34:35], v[34:35], v[128:129] op_sel_hi:[1,0]
	s_add_u32 s10, s10, 4
	s_addc_u32 s12, s12, 0
	s_add_i32 s8, s8, -1
	s_nop 0
	s_waitcnt lgkmcnt(0)
	s_barrier
	ds_read_b128 v[180:183], v130
	ds_read_b128 v[196:199], v131 offset:53248
	ds_read_b128 v[184:187], v130 offset:64
	ds_read_b128 v[200:203], v131 offset:53312
	ds_read_b128 v[188:191], v130 offset:128
	ds_read_b128 v[208:211], v131 offset:53376
	ds_read_b128 v[192:195], v130 offset:192
	ds_read_b128 v[212:215], v131 offset:53440
	ds_read_b128 v[216:219], v131
	ds_read_b128 v[220:223], v131 offset:64
	ds_read_b128 v[224:227], v131 offset:128
	ds_read_b128 v[228:231], v131 offset:192
	global_load_dwordx4 v[18:21], v[18:19], off
	global_load_dwordx4 v[22:25], v[22:23], off
	global_load_dwordx4 v[26:29], v[26:27], off
	global_load_ushort v103, v[146:147], off
	global_load_ushort v147, v[148:149], off offset:-256
	global_load_ushort v105, v[148:149], off
	global_load_ushort v146, v[148:149], off offset:256
	global_load_dword v106, v1, s[18:19]
	v_lshl_add_u64 v[108:109], v[108:109], 0, s[56:57]
	v_lshl_add_u64 v[110:111], v[110:111], 0, s[56:57]
	v_lshl_add_u64 v[114:115], v[114:115], 0, s[56:57]
	s_waitcnt lgkmcnt(10)
	v_mfma_f32_16x16x32_bf16 v[152:155], v[196:199], v[180:183], 0
	ds_read_b128 v[232:235], v133
	v_lshl_add_u64 v[116:117], v[116:117], 0, s[56:57]
	s_waitcnt lgkmcnt(9)
	v_mfma_f32_16x16x32_bf16 v[152:155], v[200:203], v[184:187], v[152:155]
	ds_read_b128 v[236:239], v133 offset:64
	v_lshl_add_u64 v[118:119], v[118:119], 0, s[4:5]
	s_waitcnt lgkmcnt(8)
	v_mfma_f32_16x16x32_bf16 v[152:155], v[208:211], v[188:191], v[152:155]
	ds_read_b128 v[240:243], v135 offset:34816
	v_lshl_add_u64 v[120:121], v[120:121], 0, s[56:57]
	s_waitcnt lgkmcnt(7)
	v_mfma_f32_16x16x32_bf16 v[152:155], v[212:215], v[192:195], v[152:155]
	ds_read_b128 v[176:179], v135 offset:34880
	v_lshl_add_u64 v[122:123], v[122:123], 0, s[4:5]
	s_waitcnt lgkmcnt(7)
	v_mfma_f32_16x16x32_bf16 v[148:151], v[216:219], v[180:183], 0
	v_lshl_add_u64 v[124:125], v[124:125], 0, s[4:5]
	s_waitcnt lgkmcnt(6)
	v_mfma_f32_16x16x32_bf16 v[148:151], v[220:223], v[184:187], v[148:151]
	v_lshl_add_u64 v[126:127], v[126:127], 0, s[4:5]
	s_waitcnt lgkmcnt(5)
	v_mfma_f32_16x16x32_bf16 v[148:151], v[224:227], v[188:191], v[148:151]
	v_and_b32_e32 v157, 0xffff0000, v99
	s_waitcnt lgkmcnt(4)
	v_mfma_f32_16x16x32_bf16 v[148:151], v[228:231], v[192:195], v[148:151]
	v_lshlrev_b32_e32 v156, 16, v99
	v_and_b32_e32 v159, 0xffff0000, v97
	v_lshlrev_b32_e32 v158, 16, v97
	v_pk_add_f32 v[152:153], v[156:157], v[152:153] neg_lo:[0,1] neg_hi:[0,1]
	v_pk_add_f32 v[154:155], v[158:159], v[154:155] neg_lo:[0,1] neg_hi:[0,1]
	v_cvt_pk_bf16_f32 v152, v152, v153
	v_cvt_pk_bf16_f32 v153, v154, v155
	ds_write_b64 v132, v[152:153]
	s_waitcnt lgkmcnt(0)
	s_barrier
	ds_read_b128 v[180:183], v134
	ds_read_b128 v[184:187], v134 offset:64
	ds_read_b128 v[188:191], v136
	ds_read_b128 v[192:195], v136 offset:64
	ds_read_b128 v[196:199], v136 offset:2304
	ds_read_b128 v[200:203], v136 offset:2368
	s_waitcnt lgkmcnt(5)
	v_mfma_f32_16x16x32_bf16 v[148:151], v[232:235], v[180:183], v[148:151]
	v_lshl_add_u64 v[152:153], s[94:95], 0, v[112:113]
	s_waitcnt lgkmcnt(4)
	v_mfma_f32_16x16x32_bf16 v[148:151], v[236:239], v[184:187], v[148:151]
	v_lshl_add_u64 v[112:113], v[112:113], 0, s[4:5]
	s_waitcnt lgkmcnt(3)
	v_mfma_f32_16x16x32_bf16 v[30:33], v[240:243], v[188:191], v[30:33]
	s_waitcnt lgkmcnt(2)
	v_mfma_f32_16x16x32_bf16 v[30:33], v[176:179], v[192:195], v[30:33]
	s_waitcnt lgkmcnt(1)
	v_mfma_f32_16x16x32_bf16 v[34:37], v[240:243], v[196:199], v[34:37]
	s_waitcnt lgkmcnt(0)
	v_mfma_f32_16x16x32_bf16 v[34:37], v[176:179], v[200:203], v[34:37]
	s_nop 0
	v_cvt_pk_bf16_f32 v97, v148, s0
	global_store_short v[152:153], v97, off offset:-512
	v_cvt_pk_bf16_f32 v97, v149, s0
	global_store_short v[152:153], v97, off offset:-256
	v_cvt_pk_bf16_f32 v97, v150, s0
	global_store_short v[152:153], v97, off
	v_cvt_pk_bf16_f32 v97, v151, s0
	global_store_short v[152:153], v97, off offset:256
	v_cvt_pk_bf16_f32 v156, v30, v31
	v_cvt_pk_bf16_f32 v157, v32, v33
	ds_write_b64 v137, v[156:157]
	v_cvt_pk_bf16_f32 v158, v34, v35
	v_cvt_pk_bf16_f32 v159, v36, v37
	ds_write_b64 v137, v[158:159] offset:4352
	s_cmp_eq_u32 s8, 0
	s_cbranch_scc0 .LBB0_286
	s_waitcnt lgkmcnt(0)
	s_barrier
	s_waitcnt vmcnt(4)
	ds_write_b128 v76, v[2:5]
	ds_write_b128 v101, v[6:9] offset:34816
	ds_write_b128 v76, v[10:13] offset:53248
	ds_write_b128 v78, v[14:17]
	ds_write_b128 v145, v[18:21] offset:34816
	ds_write_b128 v78, v[22:25] offset:53248
	ds_write_b128 v129, v[26:29]
	s_waitcnt lgkmcnt(0)
	s_barrier
	ds_read_b128 v[2:5], v131 offset:53248
	ds_read_b128 v[6:9], v130
	ds_read_b128 v[10:13], v130 offset:64
	ds_read_b128 v[14:17], v131 offset:53312
	s_waitcnt lgkmcnt(2)
	v_mfma_f32_16x16x32_bf16 v[2:5], v[2:5], v[6:9], 0
	ds_read_b128 v[18:21], v131
	ds_read_b128 v[22:25], v131 offset:64
	v_lshlrev_b32_e32 v27, 16, v147
	v_lshlrev_b32_e32 v26, 16, v103
	s_waitcnt lgkmcnt(2)
	v_mfma_f32_16x16x32_bf16 v[2:5], v[14:17], v[10:13], v[2:5]
	ds_read_b128 v[14:17], v131 offset:53376
	s_lshl_b32 s8, s11, 1
	s_add_u32 s6, s6, s8
	s_waitcnt lgkmcnt(2)
	v_mfma_f32_16x16x32_bf16 v[6:9], v[18:21], v[6:9], 0
	s_addc_u32 s7, s7, 0
	s_add_i32 s2, s2, s50
	s_cmpk_gt_i32 s2, 0xff
	s_waitcnt lgkmcnt(1)
	v_mfma_f32_16x16x32_bf16 v[6:9], v[22:25], v[10:13], v[6:9]
	ds_read_b128 v[10:13], v131 offset:53440
	ds_read_b128 v[18:21], v130 offset:128
	ds_read_b128 v[22:25], v130 offset:192
	s_waitcnt lgkmcnt(1)
	v_mfma_f32_16x16x32_bf16 v[2:5], v[14:17], v[18:21], v[2:5]
	s_waitcnt lgkmcnt(0)
	v_mfma_f32_16x16x32_bf16 v[2:5], v[10:13], v[22:25], v[2:5]
	ds_read_b128 v[10:13], v131 offset:128
	ds_read_b128 v[14:17], v131 offset:192
	s_waitcnt lgkmcnt(1)
	v_mfma_f32_16x16x32_bf16 v[6:9], v[10:13], v[18:21], v[6:9]
	s_nop 3
	v_add_f32_e64 v2, v26, -v2
	v_add_f32_e64 v3, v27, -v3
	v_lshlrev_b32_e32 v27, 16, v146
	v_lshlrev_b32_e32 v26, 16, v105
	v_pk_add_f32 v[4:5], v[26:27], v[4:5] neg_lo:[0,1] neg_hi:[0,1]
	v_cvt_pk_bf16_f32 v2, v2, v3
	v_cvt_pk_bf16_f32 v3, v4, v5
	ds_write_b64 v132, v[2:3]
	s_waitcnt lgkmcnt(0)
	s_barrier
	ds_read_b128 v[2:5], v133
	ds_read_b128 v[10:13], v134
	ds_read_b128 v[18:21], v133 offset:64
	v_mfma_f32_16x16x32_bf16 v[6:9], v[14:17], v[22:25], v[6:9]
	ds_read_b128 v[14:17], v134 offset:64
	v_mov_b32_e32 v105, v1
	s_waitcnt lgkmcnt(2)
	v_mfma_f32_16x16x32_bf16 v[2:5], v[2:5], v[10:13], v[6:9]
	s_nop 3
	v_lshl_add_u64 v[6:7], s[6:7], 0, v[0:1]
	v_lshl_add_u64 v[6:7], v[6:7], 0, v[104:105]
	s_waitcnt lgkmcnt(0)
	v_mfma_f32_16x16x32_bf16 v[2:5], v[18:21], v[14:17], v[2:5]
	s_mov_b64 s[6:7], 0xfc000
	v_lshl_add_u64 v[108:109], v[6:7], 0, s[6:7]
	v_lshl_add_u64 v[6:7], v[66:67], 1, v[108:109]
	s_waitcnt vmcnt(4)
	v_pk_mul_f32 v[20:21], v[106:107], v[32:33] op_sel_hi:[0,1]
	v_pk_mul_f32 v[18:19], v[106:107], v[30:31] op_sel_hi:[0,1]
	s_nop 1
	v_cvt_pk_bf16_f32 v2, v2, s0
	global_store_short v[6:7], v2, off
	ds_read_b128 v[6:9], v135 offset:34816
	v_cvt_pk_bf16_f32 v10, v3, s0
	v_lshl_add_u64 v[2:3], v[70:71], 1, v[108:109]
	global_store_short v[2:3], v10, off
	ds_read_b128 v[10:13], v135 offset:34880
	ds_read_b128 v[14:17], v136
	ds_read_b128 v[22:25], v136 offset:64
	s_waitcnt lgkmcnt(1)
	v_mfma_f32_16x16x32_bf16 v[14:17], v[6:9], v[14:17], v[18:21]
	s_nop 2
	ds_read_b128 v[18:21], v136 offset:2304
	ds_read_b128 v[26:29], v136 offset:2368
	v_cvt_pk_bf16_f32 v4, v4, s0
	s_waitcnt lgkmcnt(2)
	v_mfma_f32_16x16x32_bf16 v[14:17], v[10:13], v[22:25], v[14:17]
	v_mul_f32_e64 v24, v106, v36
	v_mul_f32_e64 v25, v106, v37
	v_pk_mul_f32 v[22:23], v[106:107], v[34:35] op_sel_hi:[0,1]
	v_lshl_add_u64 v[2:3], v[72:73], 1, v[108:109]
	global_store_short v[2:3], v4, off
	s_waitcnt lgkmcnt(1)
	v_mfma_f32_16x16x32_bf16 v[6:9], v[6:9], v[18:21], v[22:25]
	v_cvt_pk_bf16_f32 v4, v5, s0
	v_lshl_add_u64 v[2:3], v[74:75], 1, v[108:109]
	global_store_short v[2:3], v4, off
	s_waitcnt lgkmcnt(0)
	v_mfma_f32_16x16x32_bf16 v[2:5], v[10:13], v[26:29], v[6:9]
	s_nop 2
	v_cvt_pk_bf16_f32 v6, v14, v15
	v_cvt_pk_bf16_f32 v7, v16, v17
	s_nop 2
	v_cvt_pk_bf16_f32 v2, v2, v3
	v_cvt_pk_bf16_f32 v3, v4, v5
	ds_write_b64 v137, v[6:7]
	ds_write_b64 v137, v[2:3] offset:4352
	s_cbranch_scc0 .LBB0_282
